# back-edge rotation extended to the 3 remaining GEMM k-loops (L0 PEER scores GEMM)
# speedup vs baseline: 1.0016x; 1.0016x over previous
; DEV int tid_l() { int t = threadIdx.x; asm volatile("" : "+v"(t)); return t; }
; DEV int stage_next(int s) { return (s == 2 * GS_STAGE) ? 0 : s + GS_STAGE; }
; template <int WAIT0>
; DEV void gk_main(f32x16 (&acc)[2][2], const GTile& t, int s0) {
;   const int tid = tid_l(), lane = tid & 63, wid = __builtin_amdgcn_readfirstlane(tid >> 6), wm = wid & 1, wn = wid >> 1, l32 = lane & 31, hi = lane >> 5;
;   GK_SRC(t)
;   const int sw = (l32 >> 1) & 7;
;   int xk[4], wk[4];
; #pragma unroll
;   for (int ks = 0; ks < 4; ++ks) { const int ko = ((2 * ks + hi) ^ sw) << 4; xk[ks] = GS_A + (64 * wm + l32) * 128 + ko; wk[ks] = GS_B + (64 * wn + l32) * 128 + ko; }
;   const int nk = t.K >> 6;
;     ...
;   vm_wait_bar<WAIT0>();
;   int stc = s0, std_ = stage_next(stage_next(s0));
; #pragma nounroll
;   for (int kt = 0; kt < nk - 2; ++kt) {
;     GK_DMA(std_, kt + 2);
;     GK_COMPUTE(stc);
;     vm_wait_bar<6>();
;     stc = stage_next(stc); std_ = stage_next(std_);
;   }
.LBB0_295:
	s_cmp_lg_u32 s15, 0
	s_cbranch_scc0 .LBB0_306
	s_bitcmp0_b32 s15, 0
	s_mov_b64 s[0:1], -1
	s_cbranch_scc1 .LBB0_300
	v_mov_b32_e32 v1, v176
	s_waitcnt vmcnt(63) lgkmcnt(0)
	s_barrier
	v_readfirstlane_b32 s0, v1
	s_ashr_i32 s1, s0, 6
	v_bfe_u32 v0, v1, 3, 3
	v_and_b32_e32 v2, 31, v1
	v_lshl_or_b32 v0, s1, 3, v0
	v_lshrrev_b32_e32 v3, 1, v0
	v_and_or_b32 v6, s0, 64, v2
	s_lshr_b32 s0, s0, 1
	v_xor_b32_e32 v3, v3, v1
	s_and_b32 s0, s0, 0x1ffffc0
	v_lshlrev_b32_e32 v3, 4, v3
	v_or_b32_e32 v2, s0, v2
	s_lshl_b32 s0, s1, 10
	v_and_b32_e32 v4, 0x70, v3
	v_bfe_u32 v3, v1, 5, 1
	v_lshrrev_b32_e32 v5, 1, v1
	v_bfe_u32 v1, v1, 1, 3
	s_add_i32 s1, s0, 0
	s_add_i32 s0, s14, 0xc000
	v_bitop3_b32 v5, v3, v5, 7 bitop3:0x78
	v_bitop3_b32 v7, v3, v1, 2 bitop3:0x36
	v_bitop3_b32 v8, v3, v1, 4 bitop3:0x36
	v_bitop3_b32 v1, v3, v1, 6 bitop3:0x36
	s_cmp_lg_u32 s14, 0x18000
	v_lshlrev_b32_e32 v2, 7, v2
	v_lshlrev_b32_e32 v5, 4, v5
	v_lshlrev_b32_e32 v7, 4, v7
	v_lshlrev_b32_e32 v8, 4, v8
	v_lshlrev_b32_e32 v1, 4, v1
	s_cselect_b32 s2, s0, 0
	s_add_i32 s0, s2, 0xc000
	v_or_b32_e32 v86, v2, v5
	v_or_b32_e32 v84, v2, v7
	v_or_b32_e32 v82, v2, v8
	v_or_b32_e32 v80, v2, v1
	v_add_u32_e32 v2, 0xc0, v0
	s_cmp_lg_u32 s2, 0x18000
	v_ashrrev_i32_e32 v3, 31, v2
	s_cselect_b32 s3, s0, 0
	s_add_u32 s10, s6, 0x100
	v_lshlrev_b64 v[2:3], 11, v[2:3]
	s_addc_u32 s11, s7, 0
	v_or_b32_e32 v2, v2, v4
	v_lshl_add_u64 v[66:67], s[10:11], 0, v[2:3]
	v_add_u32_e32 v2, 0x80, v0
	v_ashrrev_i32_e32 v3, 31, v2
	v_lshlrev_b64 v[2:3], 11, v[2:3]
	v_or_b32_e32 v2, v2, v4
	v_lshlrev_b32_e32 v6, 7, v6
	v_lshl_add_u64 v[68:69], s[10:11], 0, v[2:3]
	v_add_u32_e32 v2, 64, v0
	v_or_b32_e32 v79, v1, v6
	v_ashrrev_i32_e32 v3, 31, v2
	v_ashrrev_i32_e32 v1, 31, v0
	v_lshlrev_b64 v[2:3], 11, v[2:3]
	v_lshlrev_b64 v[0:1], 11, v[0:1]
	v_or_b32_e32 v2, v2, v4
	v_or_b32_e32 v0, v0, v4
	v_lshl_add_u64 v[70:71], s[10:11], 0, v[2:3]
	v_lshl_add_u64 v[72:73], s[10:11], 0, v[0:1]
	v_readlane_b32 s10, v231, 15
	v_readlane_b32 s11, v231, 16
	v_or_b32_e32 v85, v5, v6
	v_or_b32_e32 v83, v7, v6
	v_lshl_add_u64 v[76:77], s[10:11], 0, v[0:1]
	v_mov_b32_e32 v0, 0
	v_or_b32_e32 v81, v8, v6
	v_lshl_add_u64 v[74:75], s[10:11], 0, v[2:3]
	s_mov_b64 s[10:11], 0
	s_mov_b32 s0, s14
	v_mov_b32_e32 v1, v0
	v_mov_b32_e32 v2, v0
	v_mov_b32_e32 v3, v0
	v_mov_b32_e32 v4, v0
	v_mov_b32_e32 v5, v0
	v_mov_b32_e32 v6, v0
	v_mov_b32_e32 v7, v0
	v_mov_b32_e32 v8, v0
	v_mov_b32_e32 v9, v0
	v_mov_b32_e32 v10, v0
	v_mov_b32_e32 v11, v0
	v_mov_b32_e32 v12, v0
	v_mov_b32_e32 v13, v0
	v_mov_b32_e32 v14, v0
	v_mov_b32_e32 v15, v0
	v_mov_b32_e32 v16, v0
	v_mov_b32_e32 v17, v0
	v_mov_b32_e32 v18, v0
	v_mov_b32_e32 v19, v0
	v_mov_b32_e32 v20, v0
	v_mov_b32_e32 v21, v0
	v_mov_b32_e32 v22, v0
	v_mov_b32_e32 v23, v0
	v_mov_b32_e32 v24, v0
	v_mov_b32_e32 v25, v0
	v_mov_b32_e32 v26, v0
	v_mov_b32_e32 v27, v0
	v_mov_b32_e32 v28, v0
	v_mov_b32_e32 v29, v0
	v_mov_b32_e32 v30, v0
	v_mov_b32_e32 v31, v0
	v_mov_b32_e32 v32, v0
	v_mov_b32_e32 v33, v0
	v_mov_b32_e32 v34, v0
	v_mov_b32_e32 v35, v0
	v_mov_b32_e32 v36, v0
	v_mov_b32_e32 v37, v0
	v_mov_b32_e32 v38, v0
	v_mov_b32_e32 v39, v0
	v_mov_b32_e32 v40, v0
	v_mov_b32_e32 v41, v0
	v_mov_b32_e32 v42, v0
	v_mov_b32_e32 v43, v0
	v_mov_b32_e32 v44, v0
	v_mov_b32_e32 v45, v0
	v_mov_b32_e32 v46, v0
	v_mov_b32_e32 v47, v0
	v_mov_b32_e32 v48, v0
	v_mov_b32_e32 v49, v0
	v_mov_b32_e32 v50, v0
	v_mov_b32_e32 v51, v0
	v_mov_b32_e32 v52, v0
	v_mov_b32_e32 v53, v0
	v_mov_b32_e32 v54, v0
	v_mov_b32_e32 v55, v0
	v_mov_b32_e32 v56, v0
	v_mov_b32_e32 v57, v0
	v_mov_b32_e32 v58, v0
	v_mov_b32_e32 v59, v0
	v_mov_b32_e32 v60, v0
	v_mov_b32_e32 v61, v0
	v_mov_b32_e32 v62, v0
	v_mov_b32_e32 v63, v0
	s_add_i32 s99, s0, 0
	v_add_u32_e32 v87, s99, v85
	ds_read_b128 v[88:91], v87
	ds_read_b128 v[92:95], v87 offset:4096
	v_add_u32_e32 v87, s99, v86
	ds_read_b128 v[96:99], v87 offset:16384
	ds_read_b128 v[100:103], v87 offset:20480
.LBB0_298:
	s_add_i32 s16, s1, s3
	s_mov_b32 s98, s16
	s_mov_b64 s[100:101], s[10:11]
	s_waitcnt lgkmcnt(0)
	v_add_u32_e32 v87, s99, v83
	ds_read_b128 v[236:239], v87
	ds_read_b128 v[240:243], v87 offset:4096
	v_add_u32_e32 v87, s99, v84
	ds_read_b128 v[244:247], v87 offset:16384
	ds_read_b128 v[248:251], v87 offset:20480
	v_mfma_f32_32x32x16_bf16 v[48:63], v[96:99], v[88:91], v[48:63]
	v_mfma_f32_32x32x16_bf16 v[32:47], v[96:99], v[92:95], v[32:47]
	s_mov_b32 m0, s98
	v_lshl_add_u64 v[254:255], v[76:77], 0, s[100:101]
	global_load_lds_dwordx4 v[254:255], off
	v_mfma_f32_32x32x16_bf16 v[16:31], v[100:103], v[88:91], v[16:31]
	v_mfma_f32_32x32x16_bf16 v[0:15], v[100:103], v[92:95], v[0:15]
	s_add_i32 m0, s98, 0x2000
	v_lshl_add_u64 v[254:255], v[74:75], 0, s[100:101]
	global_load_lds_dwordx4 v[254:255], off
	v_add_u32_e32 v87, s99, v81
	s_waitcnt lgkmcnt(0)
	ds_read_b128 v[88:91], v87
	ds_read_b128 v[92:95], v87 offset:4096
	v_add_u32_e32 v87, s99, v82
	ds_read_b128 v[96:99], v87 offset:16384
	ds_read_b128 v[100:103], v87 offset:20480
	v_mfma_f32_32x32x16_bf16 v[48:63], v[244:247], v[236:239], v[48:63]
	v_mfma_f32_32x32x16_bf16 v[32:47], v[244:247], v[240:243], v[32:47]
	s_add_i32 m0, s98, 0x4000
	v_lshl_add_u64 v[254:255], v[72:73], 0, s[100:101]
	global_load_lds_dwordx4 v[254:255], off
	v_mfma_f32_32x32x16_bf16 v[16:31], v[248:251], v[236:239], v[16:31]
	v_mfma_f32_32x32x16_bf16 v[0:15], v[248:251], v[240:243], v[0:15]
	s_add_i32 m0, s98, 0x6000
	v_lshl_add_u64 v[254:255], v[70:71], 0, s[100:101]
	global_load_lds_dwordx4 v[254:255], off
	v_add_u32_e32 v87, s99, v79
	s_waitcnt lgkmcnt(0)
	ds_read_b128 v[236:239], v87
	ds_read_b128 v[240:243], v87 offset:4096
	v_add_u32_e32 v87, s99, v80
	ds_read_b128 v[244:247], v87 offset:16384
	ds_read_b128 v[248:251], v87 offset:20480
	v_mfma_f32_32x32x16_bf16 v[48:63], v[96:99], v[88:91], v[48:63]
	v_mfma_f32_32x32x16_bf16 v[32:47], v[96:99], v[92:95], v[32:47]
	s_add_i32 m0, s98, 0x8000
	v_lshl_add_u64 v[254:255], v[68:69], 0, s[100:101]
	global_load_lds_dwordx4 v[254:255], off
	v_mfma_f32_32x32x16_bf16 v[16:31], v[100:103], v[88:91], v[16:31]
	v_mfma_f32_32x32x16_bf16 v[0:15], v[100:103], v[92:95], v[0:15]
	s_add_i32 m0, s98, 0xa000
	v_lshl_add_u64 v[254:255], v[66:67], 0, s[100:101]
	global_load_lds_dwordx4 v[254:255], off
	s_add_i32 s16, s0, 0xc000
	s_cmp_lg_u32 s0, 0x18000
	s_cselect_b32 s0, s16, 0
	s_add_i32 s16, s3, 0xc000
	s_waitcnt lgkmcnt(0)
	v_mfma_f32_32x32x16_bf16 v[48:63], v[244:247], v[236:239], v[48:63]
	s_cmp_lg_u32 s3, 0x18000
	s_waitcnt vmcnt(6) lgkmcnt(0)
	s_barrier
; DEV int stage_next(int s) { return (s == 2 * GS_STAGE) ? 0 : s + GS_STAGE; }
; template <int WAIT0>
; DEV void gk_main(f32x16 (&acc)[2][2], const GTile& t, int s0) {
;     ...
;   for (int kt = 0; kt < nk - 2; ++kt) {
;     GK_DMA(std_, kt + 2);
;     GK_COMPUTE(stc);
;     vm_wait_bar<6>();
;     stc = stage_next(stc); std_ = stage_next(std_);
;   }
;   GK_COMPUTE(stc);
;   vm_wait_bar<0>();
;   stc = stage_next(stc);
;   GK_COMPUTE(stc);
;   vm_wait_bar<0>();
	s_cselect_b32 s3, s16, 0
	s_add_u32 s10, s10, 0x80
	s_addc_u32 s11, s11, 0
	s_add_i32 s99, s0, 0
	v_add_u32_e32 v87, s99, v85
	ds_read_b128 v[88:91], v87
	ds_read_b128 v[92:95], v87 offset:4096
	v_add_u32_e32 v87, s99, v86
	ds_read_b128 v[96:99], v87 offset:16384
	ds_read_b128 v[100:103], v87 offset:20480
	v_mfma_f32_32x32x16_bf16 v[32:47], v[244:247], v[240:243], v[32:47]
	s_cmpk_lg_i32 s10, 0x700
	v_mfma_f32_32x32x16_bf16 v[16:31], v[248:251], v[236:239], v[16:31]
	v_mfma_f32_32x32x16_bf16 v[0:15], v[248:251], v[240:243], v[0:15]
	s_cbranch_scc1 .LBB0_298
	s_waitcnt lgkmcnt(0)
	s_add_i32 s1, s0, 0
	v_add_u32_e32 v87, s1, v86
	ds_read_b128 v[66:69], v87 offset:16384
	v_add_u32_e32 v74, s1, v85
	ds_read_b128 v[70:73], v74
	ds_read_b128 v[74:77], v74 offset:4096
	s_waitcnt lgkmcnt(0)
	v_mfma_f32_32x32x16_bf16 v[48:63], v[66:69], v[70:73], v[48:63]
	v_mfma_f32_32x32x16_bf16 v[32:47], v[66:69], v[74:77], v[32:47]
	ds_read_b128 v[66:69], v87 offset:20480
	v_add_u32_e32 v87, s1, v84
	s_waitcnt lgkmcnt(0)
	v_mfma_f32_32x32x16_bf16 v[16:31], v[66:69], v[70:73], v[16:31]
	v_mfma_f32_32x32x16_bf16 v[0:15], v[66:69], v[74:77], v[0:15]
	ds_read_b128 v[66:69], v87 offset:16384
	v_add_u32_e32 v74, s1, v83
	ds_read_b128 v[70:73], v74
	ds_read_b128 v[74:77], v74 offset:4096
	s_waitcnt lgkmcnt(0)
	v_mfma_f32_32x32x16_bf16 v[48:63], v[66:69], v[70:73], v[48:63]
	v_mfma_f32_32x32x16_bf16 v[32:47], v[66:69], v[74:77], v[32:47]
	ds_read_b128 v[66:69], v87 offset:20480
	v_add_u32_e32 v87, s1, v82
	s_waitcnt lgkmcnt(0)
	v_mfma_f32_32x32x16_bf16 v[16:31], v[66:69], v[70:73], v[16:31]
	v_mfma_f32_32x32x16_bf16 v[0:15], v[66:69], v[74:77], v[0:15]
	ds_read_b128 v[66:69], v87 offset:16384
	v_add_u32_e32 v74, s1, v81
	ds_read_b128 v[70:73], v74
	ds_read_b128 v[74:77], v74 offset:4096
	s_waitcnt lgkmcnt(0)
	v_mfma_f32_32x32x16_bf16 v[48:63], v[66:69], v[70:73], v[48:63]
	v_mfma_f32_32x32x16_bf16 v[32:47], v[66:69], v[74:77], v[32:47]
	ds_read_b128 v[66:69], v87 offset:20480
	v_add_u32_e32 v87, s1, v80
	s_waitcnt lgkmcnt(0)
	v_mfma_f32_32x32x16_bf16 v[16:31], v[66:69], v[70:73], v[16:31]
	v_mfma_f32_32x32x16_bf16 v[0:15], v[66:69], v[74:77], v[0:15]
	ds_read_b128 v[66:69], v87 offset:16384
	v_add_u32_e32 v74, s1, v79
	ds_read_b128 v[70:73], v74
	ds_read_b128 v[74:77], v74 offset:4096
	s_add_i32 s1, s0, 0xc000
	s_cmp_lg_u32 s0, 0x18000
	s_cselect_b32 s0, s1, 0
	s_waitcnt lgkmcnt(0)
	v_mfma_f32_32x32x16_bf16 v[48:63], v[66:69], v[70:73], v[48:63]
	s_add_i32 s0, s0, 0
	v_add_u32_e32 v86, s0, v86
	v_add_u32_e32 v84, s0, v84
	v_add_u32_e32 v82, s0, v82
	v_add_u32_e32 v80, s0, v80
	v_mfma_f32_32x32x16_bf16 v[32:47], v[66:69], v[74:77], v[32:47]
	ds_read_b128 v[66:69], v87 offset:20480
	s_waitcnt vmcnt(0) lgkmcnt(0)
	s_barrier
	s_waitcnt lgkmcnt(0)
	v_mfma_f32_32x32x16_bf16 v[16:31], v[66:69], v[70:73], v[16:31]
	v_mfma_f32_32x32x16_bf16 v[0:15], v[66:69], v[74:77], v[0:15]
	ds_read_b128 v[66:69], v86 offset:16384
	v_add_u32_e32 v74, s0, v85
	ds_read_b128 v[70:73], v74
	ds_read_b128 v[74:77], v74 offset:4096
	s_waitcnt lgkmcnt(0)
	v_mfma_f32_32x32x16_bf16 v[48:63], v[66:69], v[70:73], v[48:63]
	v_mfma_f32_32x32x16_bf16 v[32:47], v[66:69], v[74:77], v[32:47]
	ds_read_b128 v[66:69], v86 offset:20480
	s_waitcnt lgkmcnt(0)
	v_mfma_f32_32x32x16_bf16 v[16:31], v[66:69], v[70:73], v[16:31]
	v_mfma_f32_32x32x16_bf16 v[0:15], v[66:69], v[74:77], v[0:15]
	ds_read_b128 v[66:69], v84 offset:16384
	v_add_u32_e32 v74, s0, v83
	ds_read_b128 v[70:73], v74
	ds_read_b128 v[74:77], v74 offset:4096
	s_waitcnt lgkmcnt(0)
	v_mfma_f32_32x32x16_bf16 v[48:63], v[66:69], v[70:73], v[48:63]
	v_mfma_f32_32x32x16_bf16 v[32:47], v[66:69], v[74:77], v[32:47]
	ds_read_b128 v[66:69], v84 offset:20480
	s_waitcnt lgkmcnt(0)
	v_mfma_f32_32x32x16_bf16 v[16:31], v[66:69], v[70:73], v[16:31]
	v_mfma_f32_32x32x16_bf16 v[0:15], v[66:69], v[74:77], v[0:15]
	ds_read_b128 v[66:69], v82 offset:16384
	v_add_u32_e32 v74, s0, v81
	ds_read_b128 v[70:73], v74
	ds_read_b128 v[74:77], v74 offset:4096
	s_waitcnt lgkmcnt(0)
	v_mfma_f32_32x32x16_bf16 v[48:63], v[66:69], v[70:73], v[48:63]
	v_mfma_f32_32x32x16_bf16 v[32:47], v[66:69], v[74:77], v[32:47]
	ds_read_b128 v[66:69], v82 offset:20480
	s_waitcnt lgkmcnt(0)
	v_mfma_f32_32x32x16_bf16 v[16:31], v[66:69], v[70:73], v[16:31]
	v_mfma_f32_32x32x16_bf16 v[0:15], v[66:69], v[74:77], v[0:15]
	ds_read_b128 v[66:69], v80 offset:16384
	v_add_u32_e32 v74, s0, v79
	ds_read_b128 v[70:73], v74
	ds_read_b128 v[74:77], v74 offset:4096
	s_mov_b64 s[0:1], 0
	s_waitcnt lgkmcnt(0)
	v_mfma_f32_32x32x16_bf16 v[48:63], v[66:69], v[70:73], v[48:63]
	v_mfma_f32_32x32x16_bf16 v[32:47], v[66:69], v[74:77], v[32:47]
	ds_read_b128 v[66:69], v80 offset:20480
	s_waitcnt vmcnt(0) lgkmcnt(0)
	s_barrier
	s_waitcnt lgkmcnt(0)
	v_mfma_f32_32x32x16_bf16 v[16:31], v[66:69], v[70:73], v[16:31]
	v_mfma_f32_32x32x16_bf16 v[0:15], v[66:69], v[74:77], v[0:15]
; DEV int tid_l() { int t = threadIdx.x; asm volatile("" : "+v"(t)); return t; }
; DEV int stage_next(int s) { return (s == 2 * GS_STAGE) ? 0 : s + GS_STAGE; }
; template <int WAIT0>
; DEV void gk_main(f32x16 (&acc)[2][2], const GTile& t, int s0) {
;   const int tid = tid_l(), lane = tid & 63, wid = __builtin_amdgcn_readfirstlane(tid >> 6), wm = wid & 1, wn = wid >> 1, l32 = lane & 31, hi = lane >> 5;
;   GK_SRC(t)
;   const int sw = (l32 >> 1) & 7;
;   int xk[4], wk[4];
; #pragma unroll
;   for (int ks = 0; ks < 4; ++ks) { const int ko = ((2 * ks + hi) ^ sw) << 4; xk[ks] = GS_A + (64 * wm + l32) * 128 + ko; wk[ks] = GS_B + (64 * wn + l32) * 128 + ko; }
;   const int nk = t.K >> 6;
;     ...
;   vm_wait_bar<WAIT0>();
;   int stc = s0, std_ = stage_next(stage_next(s0));
; #pragma nounroll
;   for (int kt = 0; kt < nk - 2; ++kt) {
;     GK_DMA(std_, kt + 2);
;     GK_COMPUTE(stc);
;     vm_wait_bar<6>();
;     stc = stage_next(stc); std_ = stage_next(std_);
;   }
.LBB0_300:
	s_and_b64 vcc, exec, s[0:1]
	s_cbranch_vccz .LBB0_304
	s_nop 9
	v_mov_b32_e32 v1, v176
	s_waitcnt vmcnt(63) lgkmcnt(0)
	s_barrier
	v_readfirstlane_b32 s0, v1
	s_ashr_i32 s1, s0, 6
	v_bfe_u32 v0, v1, 3, 3
	v_and_b32_e32 v2, 31, v1
	v_lshl_or_b32 v0, s1, 3, v0
	v_lshrrev_b32_e32 v3, 1, v0
	v_and_or_b32 v6, s0, 64, v2
	s_lshr_b32 s0, s0, 1
	v_xor_b32_e32 v3, v3, v1
	s_and_b32 s0, s0, 0x1ffffc0
	v_lshlrev_b32_e32 v3, 4, v3
	v_or_b32_e32 v2, s0, v2
	s_lshl_b32 s0, s1, 10
	v_and_b32_e32 v4, 0x70, v3
	v_bfe_u32 v3, v1, 5, 1
	v_lshrrev_b32_e32 v5, 1, v1
	v_bfe_u32 v1, v1, 1, 3
	s_add_i32 s1, s0, 0
	s_add_i32 s0, s14, 0xc000
	v_bitop3_b32 v5, v3, v5, 7 bitop3:0x78
	v_bitop3_b32 v7, v3, v1, 2 bitop3:0x36
	v_bitop3_b32 v8, v3, v1, 4 bitop3:0x36
	v_bitop3_b32 v1, v3, v1, 6 bitop3:0x36
	s_cmp_lg_u32 s14, 0x18000
	v_lshlrev_b32_e32 v2, 7, v2
	v_lshlrev_b32_e32 v5, 4, v5
	v_lshlrev_b32_e32 v7, 4, v7
	v_lshlrev_b32_e32 v8, 4, v8
	v_lshlrev_b32_e32 v1, 4, v1
	s_cselect_b32 s2, s0, 0
	s_add_i32 s0, s2, 0xc000
	v_or_b32_e32 v86, v2, v5
	v_or_b32_e32 v84, v2, v7
	v_or_b32_e32 v82, v2, v8
	v_or_b32_e32 v80, v2, v1
	v_add_u32_e32 v2, 0xc0, v0
	s_cmp_lg_u32 s2, 0x18000
	v_ashrrev_i32_e32 v3, 31, v2
	s_cselect_b32 s3, s0, 0
	s_add_u32 s10, s6, 0x100
	v_lshlrev_b64 v[2:3], 11, v[2:3]
	s_addc_u32 s11, s7, 0
	v_or_b32_e32 v2, v2, v4
	v_lshl_add_u64 v[66:67], s[10:11], 0, v[2:3]
	v_add_u32_e32 v2, 0x80, v0
	v_ashrrev_i32_e32 v3, 31, v2
	v_lshlrev_b64 v[2:3], 11, v[2:3]
	v_or_b32_e32 v2, v2, v4
	v_lshlrev_b32_e32 v6, 7, v6
	v_lshl_add_u64 v[68:69], s[10:11], 0, v[2:3]
	v_add_u32_e32 v2, 64, v0
	v_or_b32_e32 v79, v1, v6
	v_ashrrev_i32_e32 v3, 31, v2
	v_ashrrev_i32_e32 v1, 31, v0
	v_lshlrev_b64 v[2:3], 11, v[2:3]
	v_lshlrev_b64 v[0:1], 11, v[0:1]
	v_or_b32_e32 v2, v2, v4
	v_or_b32_e32 v0, v0, v4
	v_lshl_add_u64 v[70:71], s[10:11], 0, v[2:3]
	v_lshl_add_u64 v[72:73], s[10:11], 0, v[0:1]
	v_readlane_b32 s10, v231, 15
	v_readlane_b32 s11, v231, 16
	v_or_b32_e32 v85, v5, v6
	v_or_b32_e32 v83, v7, v6
	v_lshl_add_u64 v[76:77], s[10:11], 0, v[0:1]
	v_mov_b32_e32 v0, 0
	v_or_b32_e32 v81, v8, v6
	v_lshl_add_u64 v[74:75], s[10:11], 0, v[2:3]
	s_mov_b64 s[10:11], 0
	s_mov_b32 s0, s14
	v_mov_b32_e32 v1, v0
	v_mov_b32_e32 v2, v0
	v_mov_b32_e32 v3, v0
	v_mov_b32_e32 v4, v0
	v_mov_b32_e32 v5, v0
	v_mov_b32_e32 v6, v0
	v_mov_b32_e32 v7, v0
	v_mov_b32_e32 v8, v0
	v_mov_b32_e32 v9, v0
	v_mov_b32_e32 v10, v0
	v_mov_b32_e32 v11, v0
	v_mov_b32_e32 v12, v0
	v_mov_b32_e32 v13, v0
	v_mov_b32_e32 v14, v0
	v_mov_b32_e32 v15, v0
	v_mov_b32_e32 v16, v0
	v_mov_b32_e32 v17, v0
	v_mov_b32_e32 v18, v0
	v_mov_b32_e32 v19, v0
	v_mov_b32_e32 v20, v0
	v_mov_b32_e32 v21, v0
	v_mov_b32_e32 v22, v0
	v_mov_b32_e32 v23, v0
	v_mov_b32_e32 v24, v0
	v_mov_b32_e32 v25, v0
	v_mov_b32_e32 v26, v0
	v_mov_b32_e32 v27, v0
	v_mov_b32_e32 v28, v0
	v_mov_b32_e32 v29, v0
	v_mov_b32_e32 v30, v0
	v_mov_b32_e32 v31, v0
	v_mov_b32_e32 v32, v0
	v_mov_b32_e32 v33, v0
	v_mov_b32_e32 v34, v0
	v_mov_b32_e32 v35, v0
	v_mov_b32_e32 v36, v0
	v_mov_b32_e32 v37, v0
	v_mov_b32_e32 v38, v0
	v_mov_b32_e32 v39, v0
	v_mov_b32_e32 v40, v0
	v_mov_b32_e32 v41, v0
	v_mov_b32_e32 v42, v0
	v_mov_b32_e32 v43, v0
	v_mov_b32_e32 v44, v0
	v_mov_b32_e32 v45, v0
	v_mov_b32_e32 v46, v0
	v_mov_b32_e32 v47, v0
	v_mov_b32_e32 v48, v0
	v_mov_b32_e32 v49, v0
	v_mov_b32_e32 v50, v0
	v_mov_b32_e32 v51, v0
	v_mov_b32_e32 v52, v0
	v_mov_b32_e32 v53, v0
	v_mov_b32_e32 v54, v0
	v_mov_b32_e32 v55, v0
	v_mov_b32_e32 v56, v0
	v_mov_b32_e32 v57, v0
	v_mov_b32_e32 v58, v0
	v_mov_b32_e32 v59, v0
	v_mov_b32_e32 v60, v0
	v_mov_b32_e32 v61, v0
	v_mov_b32_e32 v62, v0
	v_mov_b32_e32 v63, v0
	s_add_i32 s99, s0, 0
	v_add_u32_e32 v87, s99, v85
	ds_read_b128 v[88:91], v87
	ds_read_b128 v[92:95], v87 offset:4096
	v_add_u32_e32 v87, s99, v86
	ds_read_b128 v[96:99], v87 offset:16384
	ds_read_b128 v[100:103], v87 offset:20480
.LBB0_302:
	s_add_i32 s16, s1, s3
	s_mov_b32 s98, s16
	s_mov_b64 s[100:101], s[10:11]
	s_waitcnt lgkmcnt(0)
	v_add_u32_e32 v87, s99, v83
	ds_read_b128 v[236:239], v87
	ds_read_b128 v[240:243], v87 offset:4096
	v_add_u32_e32 v87, s99, v84
	ds_read_b128 v[244:247], v87 offset:16384
	ds_read_b128 v[248:251], v87 offset:20480
	v_mfma_f32_32x32x16_bf16 v[48:63], v[96:99], v[88:91], v[48:63]
	v_mfma_f32_32x32x16_bf16 v[32:47], v[96:99], v[92:95], v[32:47]
	s_mov_b32 m0, s98
	v_lshl_add_u64 v[254:255], v[76:77], 0, s[100:101]
	global_load_lds_dwordx4 v[254:255], off
	v_mfma_f32_32x32x16_bf16 v[16:31], v[100:103], v[88:91], v[16:31]
	v_mfma_f32_32x32x16_bf16 v[0:15], v[100:103], v[92:95], v[0:15]
	s_add_i32 m0, s98, 0x2000
	v_lshl_add_u64 v[254:255], v[74:75], 0, s[100:101]
	global_load_lds_dwordx4 v[254:255], off
	v_add_u32_e32 v87, s99, v81
	s_waitcnt lgkmcnt(0)
	ds_read_b128 v[88:91], v87
	ds_read_b128 v[92:95], v87 offset:4096
	v_add_u32_e32 v87, s99, v82
	ds_read_b128 v[96:99], v87 offset:16384
	ds_read_b128 v[100:103], v87 offset:20480
	v_mfma_f32_32x32x16_bf16 v[48:63], v[244:247], v[236:239], v[48:63]
	v_mfma_f32_32x32x16_bf16 v[32:47], v[244:247], v[240:243], v[32:47]
	s_add_i32 m0, s98, 0x4000
	v_lshl_add_u64 v[254:255], v[72:73], 0, s[100:101]
	global_load_lds_dwordx4 v[254:255], off
	v_mfma_f32_32x32x16_bf16 v[16:31], v[248:251], v[236:239], v[16:31]
	v_mfma_f32_32x32x16_bf16 v[0:15], v[248:251], v[240:243], v[0:15]
	s_add_i32 m0, s98, 0x6000
	v_lshl_add_u64 v[254:255], v[70:71], 0, s[100:101]
	global_load_lds_dwordx4 v[254:255], off
	v_add_u32_e32 v87, s99, v79
	s_waitcnt lgkmcnt(0)
	ds_read_b128 v[236:239], v87
	ds_read_b128 v[240:243], v87 offset:4096
	v_add_u32_e32 v87, s99, v80
	ds_read_b128 v[244:247], v87 offset:16384
	ds_read_b128 v[248:251], v87 offset:20480
	v_mfma_f32_32x32x16_bf16 v[48:63], v[96:99], v[88:91], v[48:63]
	v_mfma_f32_32x32x16_bf16 v[32:47], v[96:99], v[92:95], v[32:47]
	s_add_i32 m0, s98, 0x8000
	v_lshl_add_u64 v[254:255], v[68:69], 0, s[100:101]
	global_load_lds_dwordx4 v[254:255], off
	v_mfma_f32_32x32x16_bf16 v[16:31], v[100:103], v[88:91], v[16:31]
	v_mfma_f32_32x32x16_bf16 v[0:15], v[100:103], v[92:95], v[0:15]
	s_add_i32 m0, s98, 0xa000
	v_lshl_add_u64 v[254:255], v[66:67], 0, s[100:101]
	global_load_lds_dwordx4 v[254:255], off
	s_add_i32 s16, s0, 0xc000
	s_cmp_lg_u32 s0, 0x18000
	s_cselect_b32 s0, s16, 0
	s_add_i32 s16, s3, 0xc000
	s_waitcnt lgkmcnt(0)
	v_mfma_f32_32x32x16_bf16 v[48:63], v[244:247], v[236:239], v[48:63]
	s_cmp_lg_u32 s3, 0x18000
	s_waitcnt vmcnt(6) lgkmcnt(0)
	s_barrier
; DEV int stage_next(int s) { return (s == 2 * GS_STAGE) ? 0 : s + GS_STAGE; }
; template <int WAIT0>
; DEV void gk_main(f32x16 (&acc)[2][2], const GTile& t, int s0) {
;     ...
;   for (int kt = 0; kt < nk - 2; ++kt) {
;     GK_DMA(std_, kt + 2);
;     GK_COMPUTE(stc);
;     vm_wait_bar<6>();
;     stc = stage_next(stc); std_ = stage_next(std_);
;   }
;   GK_COMPUTE(stc);
;   vm_wait_bar<0>();
;   stc = stage_next(stc);
;   GK_COMPUTE(stc);
;   vm_wait_bar<0>();
	s_cselect_b32 s3, s16, 0
	s_add_u32 s10, s10, 0x80
	s_addc_u32 s11, s11, 0
	s_add_i32 s99, s0, 0
	v_add_u32_e32 v87, s99, v85
	ds_read_b128 v[88:91], v87
	ds_read_b128 v[92:95], v87 offset:4096
	v_add_u32_e32 v87, s99, v86
	ds_read_b128 v[96:99], v87 offset:16384
	ds_read_b128 v[100:103], v87 offset:20480
	v_mfma_f32_32x32x16_bf16 v[32:47], v[244:247], v[240:243], v[32:47]
	s_cmpk_lg_i32 s10, 0x700
	v_mfma_f32_32x32x16_bf16 v[16:31], v[248:251], v[236:239], v[16:31]
	v_mfma_f32_32x32x16_bf16 v[0:15], v[248:251], v[240:243], v[0:15]
	s_cbranch_scc1 .LBB0_302
	s_waitcnt lgkmcnt(0)
	s_add_i32 s1, s0, 0
	v_add_u32_e32 v87, s1, v86
	ds_read_b128 v[66:69], v87 offset:16384
	v_add_u32_e32 v74, s1, v85
	ds_read_b128 v[70:73], v74
	ds_read_b128 v[74:77], v74 offset:4096
	s_waitcnt lgkmcnt(0)
	v_mfma_f32_32x32x16_bf16 v[48:63], v[66:69], v[70:73], v[48:63]
	v_mfma_f32_32x32x16_bf16 v[32:47], v[66:69], v[74:77], v[32:47]
	ds_read_b128 v[66:69], v87 offset:20480
	v_add_u32_e32 v87, s1, v84
	s_waitcnt lgkmcnt(0)
	v_mfma_f32_32x32x16_bf16 v[16:31], v[66:69], v[70:73], v[16:31]
	v_mfma_f32_32x32x16_bf16 v[0:15], v[66:69], v[74:77], v[0:15]
	ds_read_b128 v[66:69], v87 offset:16384
	v_add_u32_e32 v74, s1, v83
	ds_read_b128 v[70:73], v74
	ds_read_b128 v[74:77], v74 offset:4096
	s_waitcnt lgkmcnt(0)
	v_mfma_f32_32x32x16_bf16 v[48:63], v[66:69], v[70:73], v[48:63]
	v_mfma_f32_32x32x16_bf16 v[32:47], v[66:69], v[74:77], v[32:47]
	ds_read_b128 v[66:69], v87 offset:20480
	v_add_u32_e32 v87, s1, v82
	s_waitcnt lgkmcnt(0)
	v_mfma_f32_32x32x16_bf16 v[16:31], v[66:69], v[70:73], v[16:31]
	v_mfma_f32_32x32x16_bf16 v[0:15], v[66:69], v[74:77], v[0:15]
	ds_read_b128 v[66:69], v87 offset:16384
	v_add_u32_e32 v74, s1, v81
	ds_read_b128 v[70:73], v74
	ds_read_b128 v[74:77], v74 offset:4096
	s_waitcnt lgkmcnt(0)
	v_mfma_f32_32x32x16_bf16 v[48:63], v[66:69], v[70:73], v[48:63]
	v_mfma_f32_32x32x16_bf16 v[32:47], v[66:69], v[74:77], v[32:47]
	ds_read_b128 v[66:69], v87 offset:20480
	v_add_u32_e32 v87, s1, v80
	s_waitcnt lgkmcnt(0)
	v_mfma_f32_32x32x16_bf16 v[16:31], v[66:69], v[70:73], v[16:31]
	v_mfma_f32_32x32x16_bf16 v[0:15], v[66:69], v[74:77], v[0:15]
	ds_read_b128 v[66:69], v87 offset:16384
	v_add_u32_e32 v74, s1, v79
	ds_read_b128 v[70:73], v74
	ds_read_b128 v[74:77], v74 offset:4096
	s_add_i32 s1, s0, 0xc000
	s_cmp_lg_u32 s0, 0x18000
	s_cselect_b32 s0, s1, 0
	s_waitcnt lgkmcnt(0)
	v_mfma_f32_32x32x16_bf16 v[48:63], v[66:69], v[70:73], v[48:63]
	s_add_i32 s0, s0, 0
	v_add_u32_e32 v86, s0, v86
	v_add_u32_e32 v84, s0, v84
	v_add_u32_e32 v82, s0, v82
	v_add_u32_e32 v80, s0, v80
	v_mfma_f32_32x32x16_bf16 v[32:47], v[66:69], v[74:77], v[32:47]
	ds_read_b128 v[66:69], v87 offset:20480
	s_waitcnt vmcnt(0) lgkmcnt(0)
	s_barrier
	s_waitcnt lgkmcnt(0)
	v_mfma_f32_32x32x16_bf16 v[16:31], v[66:69], v[70:73], v[16:31]
	v_mfma_f32_32x32x16_bf16 v[0:15], v[66:69], v[74:77], v[0:15]
	ds_read_b128 v[66:69], v86 offset:16384
	v_add_u32_e32 v74, s0, v85
	ds_read_b128 v[70:73], v74
	ds_read_b128 v[74:77], v74 offset:4096
	s_waitcnt lgkmcnt(0)
	v_mfma_f32_32x32x16_bf16 v[48:63], v[66:69], v[70:73], v[48:63]
	v_mfma_f32_32x32x16_bf16 v[32:47], v[66:69], v[74:77], v[32:47]
	ds_read_b128 v[66:69], v86 offset:20480
	s_waitcnt lgkmcnt(0)
	v_mfma_f32_32x32x16_bf16 v[16:31], v[66:69], v[70:73], v[16:31]
	v_mfma_f32_32x32x16_bf16 v[0:15], v[66:69], v[74:77], v[0:15]
	ds_read_b128 v[66:69], v84 offset:16384
	v_add_u32_e32 v74, s0, v83
	ds_read_b128 v[70:73], v74
	ds_read_b128 v[74:77], v74 offset:4096
	s_waitcnt lgkmcnt(0)
	v_mfma_f32_32x32x16_bf16 v[48:63], v[66:69], v[70:73], v[48:63]
	v_mfma_f32_32x32x16_bf16 v[32:47], v[66:69], v[74:77], v[32:47]
	ds_read_b128 v[66:69], v84 offset:20480
	s_waitcnt lgkmcnt(0)
	v_mfma_f32_32x32x16_bf16 v[16:31], v[66:69], v[70:73], v[16:31]
	v_mfma_f32_32x32x16_bf16 v[0:15], v[66:69], v[74:77], v[0:15]
	ds_read_b128 v[66:69], v82 offset:16384
	v_add_u32_e32 v74, s0, v81
	ds_read_b128 v[70:73], v74
	ds_read_b128 v[74:77], v74 offset:4096
	s_waitcnt lgkmcnt(0)
	v_mfma_f32_32x32x16_bf16 v[48:63], v[66:69], v[70:73], v[48:63]
	v_mfma_f32_32x32x16_bf16 v[32:47], v[66:69], v[74:77], v[32:47]
	ds_read_b128 v[66:69], v82 offset:20480
	s_waitcnt lgkmcnt(0)
	v_mfma_f32_32x32x16_bf16 v[16:31], v[66:69], v[70:73], v[16:31]
	v_mfma_f32_32x32x16_bf16 v[0:15], v[66:69], v[74:77], v[0:15]
	ds_read_b128 v[66:69], v80 offset:16384
	v_add_u32_e32 v74, s0, v79
	ds_read_b128 v[70:73], v74
	ds_read_b128 v[74:77], v74 offset:4096
	s_waitcnt lgkmcnt(0)
	v_mfma_f32_32x32x16_bf16 v[48:63], v[66:69], v[70:73], v[48:63]
	v_mfma_f32_32x32x16_bf16 v[32:47], v[66:69], v[74:77], v[32:47]
	ds_read_b128 v[66:69], v80 offset:20480
	s_waitcnt vmcnt(0) lgkmcnt(0)
	s_barrier
	s_waitcnt lgkmcnt(0)
	v_mfma_f32_32x32x16_bf16 v[16:31], v[66:69], v[70:73], v[16:31]
	v_mfma_f32_32x32x16_bf16 v[0:15], v[66:69], v[74:77], v[0:15]

; DEV int tid_l() { int t = threadIdx.x; asm volatile("" : "+v"(t)); return t; }
; DEV int stage_next(int s) { return (s == 2 * GS_STAGE) ? 0 : s + GS_STAGE; }
; template <int WAIT0>
; DEV void gk_main(f32x16 (&acc)[2][2], const GTile& t, int s0) {
;   const int tid = tid_l(), lane = tid & 63, wid = __builtin_amdgcn_readfirstlane(tid >> 6), wm = wid & 1, wn = wid >> 1, l32 = lane & 31, hi = lane >> 5;
;   GK_SRC(t)
;   const int sw = (l32 >> 1) & 7;
;   int xk[4], wk[4];
; #pragma unroll
;   for (int ks = 0; ks < 4; ++ks) { const int ko = ((2 * ks + hi) ^ sw) << 4; xk[ks] = GS_A + (64 * wm + l32) * 128 + ko; wk[ks] = GS_B + (64 * wn + l32) * 128 + ko; }
;   const int nk = t.K >> 6;
;     ...
;   vm_wait_bar<WAIT0>();
;   int stc = s0, std_ = stage_next(stage_next(s0));
; #pragma nounroll
;   for (int kt = 0; kt < nk - 2; ++kt) {
;     GK_DMA(std_, kt + 2);
;     GK_COMPUTE(stc);
;     vm_wait_bar<6>();
;     stc = stage_next(stc); std_ = stage_next(std_);
;   }
.LBB0_306:
.LBB0_307:
	s_nop 10
	v_mov_b32_e32 v1, v176
	s_waitcnt vmcnt(6) lgkmcnt(0)
	s_barrier
	v_readfirstlane_b32 s0, v1
	s_ashr_i32 s1, s0, 6
	v_bfe_u32 v0, v1, 3, 3
	v_and_b32_e32 v2, 31, v1
	v_lshl_or_b32 v0, s1, 3, v0
	v_lshrrev_b32_e32 v3, 1, v0
	v_and_or_b32 v6, s0, 64, v2
	s_lshr_b32 s0, s0, 1
	v_xor_b32_e32 v3, v3, v1
	s_and_b32 s0, s0, 0x1ffffc0
	v_lshlrev_b32_e32 v3, 4, v3
	v_or_b32_e32 v2, s0, v2
	s_lshl_b32 s0, s1, 10
	v_and_b32_e32 v4, 0x70, v3
	v_bfe_u32 v3, v1, 5, 1
	v_lshrrev_b32_e32 v5, 1, v1
	v_bfe_u32 v1, v1, 1, 3
	s_add_i32 s0, s0, 0
	s_add_i32 s1, s14, 0xc000
	v_bitop3_b32 v5, v3, v5, 7 bitop3:0x78
	v_bitop3_b32 v7, v3, v1, 2 bitop3:0x36
	v_bitop3_b32 v8, v3, v1, 4 bitop3:0x36
	v_bitop3_b32 v1, v3, v1, 6 bitop3:0x36
	s_cmp_lg_u32 s14, 0x18000
	v_lshlrev_b32_e32 v2, 7, v2
	v_lshlrev_b32_e32 v5, 4, v5
	v_lshlrev_b32_e32 v7, 4, v7
	v_lshlrev_b32_e32 v8, 4, v8
	v_lshlrev_b32_e32 v1, 4, v1
	s_cselect_b32 s2, s1, 0
	s_add_i32 s1, s2, 0xc000
	v_or_b32_e32 v86, v2, v5
	v_or_b32_e32 v84, v2, v7
	v_or_b32_e32 v82, v2, v8
	v_or_b32_e32 v80, v2, v1
	v_add_u32_e32 v2, 0xc0, v0
	s_cmp_lg_u32 s2, 0x18000
	v_ashrrev_i32_e32 v3, 31, v2
	s_cselect_b32 s1, s1, 0
	s_add_u32 s10, s6, 0x100
	v_lshlrev_b64 v[2:3], 11, v[2:3]
	s_addc_u32 s11, s7, 0
	v_or_b32_e32 v2, v2, v4
	v_lshl_add_u64 v[66:67], s[10:11], 0, v[2:3]
	v_add_u32_e32 v2, 0x80, v0
	v_ashrrev_i32_e32 v3, 31, v2
	v_lshlrev_b64 v[2:3], 11, v[2:3]
	v_or_b32_e32 v2, v2, v4
	v_lshlrev_b32_e32 v6, 7, v6
	v_lshl_add_u64 v[68:69], s[10:11], 0, v[2:3]
	v_add_u32_e32 v2, 64, v0
	v_or_b32_e32 v79, v1, v6
	v_ashrrev_i32_e32 v3, 31, v2
	v_ashrrev_i32_e32 v1, 31, v0
	v_lshlrev_b64 v[2:3], 11, v[2:3]
	v_lshlrev_b64 v[0:1], 11, v[0:1]
	v_or_b32_e32 v2, v2, v4
	v_or_b32_e32 v0, v0, v4
	v_lshl_add_u64 v[70:71], s[10:11], 0, v[2:3]
	v_lshl_add_u64 v[72:73], s[10:11], 0, v[0:1]
	v_readlane_b32 s10, v231, 15
	v_readlane_b32 s11, v231, 16
	v_or_b32_e32 v85, v5, v6
	v_or_b32_e32 v83, v7, v6
	v_lshl_add_u64 v[76:77], s[10:11], 0, v[0:1]
	v_mov_b32_e32 v0, 0
	v_or_b32_e32 v81, v8, v6
	v_lshl_add_u64 v[74:75], s[10:11], 0, v[2:3]
	s_mov_b64 s[10:11], 0
	v_mov_b32_e32 v1, v0
	v_mov_b32_e32 v2, v0
	v_mov_b32_e32 v3, v0
	v_mov_b32_e32 v4, v0
	v_mov_b32_e32 v5, v0
	v_mov_b32_e32 v6, v0
	v_mov_b32_e32 v7, v0
	v_mov_b32_e32 v8, v0
	v_mov_b32_e32 v9, v0
	v_mov_b32_e32 v10, v0
	v_mov_b32_e32 v11, v0
	v_mov_b32_e32 v12, v0
	v_mov_b32_e32 v13, v0
	v_mov_b32_e32 v14, v0
	v_mov_b32_e32 v15, v0
	v_mov_b32_e32 v16, v0
	v_mov_b32_e32 v17, v0
	v_mov_b32_e32 v18, v0
	v_mov_b32_e32 v19, v0
	v_mov_b32_e32 v20, v0
	v_mov_b32_e32 v21, v0
	v_mov_b32_e32 v22, v0
	v_mov_b32_e32 v23, v0
	v_mov_b32_e32 v24, v0
	v_mov_b32_e32 v25, v0
	v_mov_b32_e32 v26, v0
	v_mov_b32_e32 v27, v0
	v_mov_b32_e32 v28, v0
	v_mov_b32_e32 v29, v0
	v_mov_b32_e32 v30, v0
	v_mov_b32_e32 v31, v0
	v_mov_b32_e32 v32, v0
	v_mov_b32_e32 v33, v0
	v_mov_b32_e32 v34, v0
	v_mov_b32_e32 v35, v0
	v_mov_b32_e32 v36, v0
	v_mov_b32_e32 v37, v0
	v_mov_b32_e32 v38, v0
	v_mov_b32_e32 v39, v0
	v_mov_b32_e32 v40, v0
	v_mov_b32_e32 v41, v0
	v_mov_b32_e32 v42, v0
	v_mov_b32_e32 v43, v0
	v_mov_b32_e32 v44, v0
	v_mov_b32_e32 v45, v0
	v_mov_b32_e32 v46, v0
	v_mov_b32_e32 v47, v0
	v_mov_b32_e32 v48, v0
	v_mov_b32_e32 v49, v0
	v_mov_b32_e32 v50, v0
	v_mov_b32_e32 v51, v0
	v_mov_b32_e32 v52, v0
	v_mov_b32_e32 v53, v0
	v_mov_b32_e32 v54, v0
	v_mov_b32_e32 v55, v0
	v_mov_b32_e32 v56, v0
	v_mov_b32_e32 v57, v0
	v_mov_b32_e32 v58, v0
	v_mov_b32_e32 v59, v0
	v_mov_b32_e32 v60, v0
	v_mov_b32_e32 v61, v0
	v_mov_b32_e32 v62, v0
	v_mov_b32_e32 v63, v0
	s_add_i32 s99, s14, 0
	v_add_u32_e32 v87, s99, v85
	ds_read_b128 v[88:91], v87
	ds_read_b128 v[92:95], v87 offset:4096
	v_add_u32_e32 v87, s99, v86
	ds_read_b128 v[96:99], v87 offset:16384
	ds_read_b128 v[100:103], v87 offset:20480
.LBB0_308:
	s_add_i32 s3, s0, s1
	s_mov_b32 s98, s3
	s_mov_b64 s[100:101], s[10:11]
	s_waitcnt lgkmcnt(0)
	v_add_u32_e32 v87, s99, v83
	ds_read_b128 v[236:239], v87
	ds_read_b128 v[240:243], v87 offset:4096
	v_add_u32_e32 v87, s99, v84
	ds_read_b128 v[244:247], v87 offset:16384
	ds_read_b128 v[248:251], v87 offset:20480
	v_mfma_f32_32x32x16_bf16 v[48:63], v[96:99], v[88:91], v[48:63]
	v_mfma_f32_32x32x16_bf16 v[32:47], v[96:99], v[92:95], v[32:47]
	s_mov_b32 m0, s98
	v_lshl_add_u64 v[254:255], v[76:77], 0, s[100:101]
	global_load_lds_dwordx4 v[254:255], off
	v_mfma_f32_32x32x16_bf16 v[16:31], v[100:103], v[88:91], v[16:31]
	v_mfma_f32_32x32x16_bf16 v[0:15], v[100:103], v[92:95], v[0:15]
	s_add_i32 m0, s98, 0x2000
	v_lshl_add_u64 v[254:255], v[74:75], 0, s[100:101]
	global_load_lds_dwordx4 v[254:255], off
	v_add_u32_e32 v87, s99, v81
	s_waitcnt lgkmcnt(0)
	ds_read_b128 v[88:91], v87
	ds_read_b128 v[92:95], v87 offset:4096
	v_add_u32_e32 v87, s99, v82
	ds_read_b128 v[96:99], v87 offset:16384
	ds_read_b128 v[100:103], v87 offset:20480
	v_mfma_f32_32x32x16_bf16 v[48:63], v[244:247], v[236:239], v[48:63]
	v_mfma_f32_32x32x16_bf16 v[32:47], v[244:247], v[240:243], v[32:47]
	s_add_i32 m0, s98, 0x4000
	v_lshl_add_u64 v[254:255], v[72:73], 0, s[100:101]
	global_load_lds_dwordx4 v[254:255], off
	v_mfma_f32_32x32x16_bf16 v[16:31], v[248:251], v[236:239], v[16:31]
	v_mfma_f32_32x32x16_bf16 v[0:15], v[248:251], v[240:243], v[0:15]
	s_add_i32 m0, s98, 0x6000
	v_lshl_add_u64 v[254:255], v[70:71], 0, s[100:101]
	global_load_lds_dwordx4 v[254:255], off
	v_add_u32_e32 v87, s99, v79
	s_waitcnt lgkmcnt(0)
	ds_read_b128 v[236:239], v87
	ds_read_b128 v[240:243], v87 offset:4096
	v_add_u32_e32 v87, s99, v80
	ds_read_b128 v[244:247], v87 offset:16384
	ds_read_b128 v[248:251], v87 offset:20480
	v_mfma_f32_32x32x16_bf16 v[48:63], v[96:99], v[88:91], v[48:63]
	v_mfma_f32_32x32x16_bf16 v[32:47], v[96:99], v[92:95], v[32:47]
	s_add_i32 m0, s98, 0x8000
	v_lshl_add_u64 v[254:255], v[68:69], 0, s[100:101]
	global_load_lds_dwordx4 v[254:255], off
	v_mfma_f32_32x32x16_bf16 v[16:31], v[100:103], v[88:91], v[16:31]
	v_mfma_f32_32x32x16_bf16 v[0:15], v[100:103], v[92:95], v[0:15]
	s_add_i32 m0, s98, 0xa000
	v_lshl_add_u64 v[254:255], v[66:67], 0, s[100:101]
	global_load_lds_dwordx4 v[254:255], off
	s_add_i32 s3, s14, 0xc000
	s_cmp_lg_u32 s14, 0x18000
	s_cselect_b32 s14, s3, 0
	s_add_i32 s3, s1, 0xc000
	s_waitcnt lgkmcnt(0)
	v_mfma_f32_32x32x16_bf16 v[48:63], v[244:247], v[236:239], v[48:63]
	s_cmp_lg_u32 s1, 0x18000
	s_waitcnt vmcnt(6) lgkmcnt(0)
	s_barrier
; DEV int stage_next(int s) { return (s == 2 * GS_STAGE) ? 0 : s + GS_STAGE; }
; template <int WAIT0>
; DEV void gk_main(f32x16 (&acc)[2][2], const GTile& t, int s0) {
;     ...
;   for (int kt = 0; kt < nk - 2; ++kt) {
;     GK_DMA(std_, kt + 2);
;     GK_COMPUTE(stc);
;     vm_wait_bar<6>();
;     stc = stage_next(stc); std_ = stage_next(std_);
;   }
;   GK_COMPUTE(stc);
;   vm_wait_bar<0>();
;   stc = stage_next(stc);
;   GK_COMPUTE(stc);
;   vm_wait_bar<0>();
	s_cselect_b32 s1, s3, 0
	s_add_u32 s10, s10, 0x80
	s_addc_u32 s11, s11, 0
	s_add_i32 s99, s14, 0
	v_add_u32_e32 v87, s99, v85
	ds_read_b128 v[88:91], v87
	ds_read_b128 v[92:95], v87 offset:4096
	v_add_u32_e32 v87, s99, v86
	ds_read_b128 v[96:99], v87 offset:16384
	ds_read_b128 v[100:103], v87 offset:20480
	v_mfma_f32_32x32x16_bf16 v[32:47], v[244:247], v[240:243], v[32:47]
	s_cmpk_lg_i32 s10, 0x700
	v_mfma_f32_32x32x16_bf16 v[16:31], v[248:251], v[236:239], v[16:31]
	v_mfma_f32_32x32x16_bf16 v[0:15], v[248:251], v[240:243], v[0:15]
	s_cbranch_scc1 .LBB0_308
	s_waitcnt lgkmcnt(0)
	s_add_i32 s0, s14, 0
	v_add_u32_e32 v87, s0, v86
	ds_read_b128 v[66:69], v87 offset:16384
	v_add_u32_e32 v74, s0, v85
	ds_read_b128 v[70:73], v74
	ds_read_b128 v[74:77], v74 offset:4096
	s_waitcnt lgkmcnt(0)
	v_mfma_f32_32x32x16_bf16 v[48:63], v[66:69], v[70:73], v[48:63]
	v_mfma_f32_32x32x16_bf16 v[32:47], v[66:69], v[74:77], v[32:47]
	ds_read_b128 v[66:69], v87 offset:20480
	v_add_u32_e32 v87, s0, v84
	s_waitcnt lgkmcnt(0)
	v_mfma_f32_32x32x16_bf16 v[16:31], v[66:69], v[70:73], v[16:31]
	v_mfma_f32_32x32x16_bf16 v[0:15], v[66:69], v[74:77], v[0:15]
	ds_read_b128 v[66:69], v87 offset:16384
	v_add_u32_e32 v74, s0, v83
	ds_read_b128 v[70:73], v74
	ds_read_b128 v[74:77], v74 offset:4096
	s_waitcnt lgkmcnt(0)
	v_mfma_f32_32x32x16_bf16 v[48:63], v[66:69], v[70:73], v[48:63]
	v_mfma_f32_32x32x16_bf16 v[32:47], v[66:69], v[74:77], v[32:47]
	ds_read_b128 v[66:69], v87 offset:20480
	v_add_u32_e32 v87, s0, v82
	s_waitcnt lgkmcnt(0)
	v_mfma_f32_32x32x16_bf16 v[16:31], v[66:69], v[70:73], v[16:31]
	v_mfma_f32_32x32x16_bf16 v[0:15], v[66:69], v[74:77], v[0:15]
	ds_read_b128 v[66:69], v87 offset:16384
	v_add_u32_e32 v74, s0, v81
	ds_read_b128 v[70:73], v74
	ds_read_b128 v[74:77], v74 offset:4096
	s_waitcnt lgkmcnt(0)
	v_mfma_f32_32x32x16_bf16 v[48:63], v[66:69], v[70:73], v[48:63]
	v_mfma_f32_32x32x16_bf16 v[32:47], v[66:69], v[74:77], v[32:47]
	ds_read_b128 v[66:69], v87 offset:20480
	v_add_u32_e32 v87, s0, v80
	s_waitcnt lgkmcnt(0)
	v_mfma_f32_32x32x16_bf16 v[16:31], v[66:69], v[70:73], v[16:31]
	v_mfma_f32_32x32x16_bf16 v[0:15], v[66:69], v[74:77], v[0:15]
	ds_read_b128 v[66:69], v87 offset:16384
	v_add_u32_e32 v74, s0, v79
	ds_read_b128 v[70:73], v74
	ds_read_b128 v[74:77], v74 offset:4096
	s_add_i32 s0, s14, 0xc000
	s_cmp_lg_u32 s14, 0x18000
	s_cselect_b32 s0, s0, 0
	s_waitcnt lgkmcnt(0)
	v_mfma_f32_32x32x16_bf16 v[48:63], v[66:69], v[70:73], v[48:63]
	s_add_i32 s0, s0, 0
	v_add_u32_e32 v86, s0, v86
	v_add_u32_e32 v84, s0, v84
	v_add_u32_e32 v82, s0, v82
	v_add_u32_e32 v80, s0, v80
	v_mfma_f32_32x32x16_bf16 v[32:47], v[66:69], v[74:77], v[32:47]
	ds_read_b128 v[66:69], v87 offset:20480
	s_waitcnt vmcnt(0) lgkmcnt(0)
	s_barrier
	s_waitcnt lgkmcnt(0)
	v_mfma_f32_32x32x16_bf16 v[16:31], v[66:69], v[70:73], v[16:31]
	v_mfma_f32_32x32x16_bf16 v[0:15], v[66:69], v[74:77], v[0:15]
	ds_read_b128 v[66:69], v86 offset:16384
	v_add_u32_e32 v74, s0, v85
	ds_read_b128 v[70:73], v74
	ds_read_b128 v[74:77], v74 offset:4096
	s_waitcnt lgkmcnt(0)
	v_mfma_f32_32x32x16_bf16 v[48:63], v[66:69], v[70:73], v[48:63]
	v_mfma_f32_32x32x16_bf16 v[32:47], v[66:69], v[74:77], v[32:47]
	ds_read_b128 v[66:69], v86 offset:20480
	s_waitcnt lgkmcnt(0)
	v_mfma_f32_32x32x16_bf16 v[16:31], v[66:69], v[70:73], v[16:31]
	v_mfma_f32_32x32x16_bf16 v[0:15], v[66:69], v[74:77], v[0:15]
	ds_read_b128 v[66:69], v84 offset:16384
	v_add_u32_e32 v74, s0, v83
	ds_read_b128 v[70:73], v74
	ds_read_b128 v[74:77], v74 offset:4096
	s_waitcnt lgkmcnt(0)
	v_mfma_f32_32x32x16_bf16 v[48:63], v[66:69], v[70:73], v[48:63]
	v_mfma_f32_32x32x16_bf16 v[32:47], v[66:69], v[74:77], v[32:47]
	ds_read_b128 v[66:69], v84 offset:20480
	s_waitcnt lgkmcnt(0)
	v_mfma_f32_32x32x16_bf16 v[16:31], v[66:69], v[70:73], v[16:31]
	v_mfma_f32_32x32x16_bf16 v[0:15], v[66:69], v[74:77], v[0:15]
	ds_read_b128 v[66:69], v82 offset:16384
	v_add_u32_e32 v74, s0, v81
	ds_read_b128 v[70:73], v74
	ds_read_b128 v[74:77], v74 offset:4096
	s_waitcnt lgkmcnt(0)
	v_mfma_f32_32x32x16_bf16 v[48:63], v[66:69], v[70:73], v[48:63]
	v_mfma_f32_32x32x16_bf16 v[32:47], v[66:69], v[74:77], v[32:47]
	ds_read_b128 v[66:69], v82 offset:20480
	s_waitcnt lgkmcnt(0)
	v_mfma_f32_32x32x16_bf16 v[16:31], v[66:69], v[70:73], v[16:31]
	v_mfma_f32_32x32x16_bf16 v[0:15], v[66:69], v[74:77], v[0:15]
	ds_read_b128 v[66:69], v80 offset:16384
	v_add_u32_e32 v74, s0, v79
	ds_read_b128 v[70:73], v74
	ds_read_b128 v[74:77], v74 offset:4096
	s_waitcnt lgkmcnt(0)
	v_mfma_f32_32x32x16_bf16 v[48:63], v[66:69], v[70:73], v[48:63]
	v_mfma_f32_32x32x16_bf16 v[32:47], v[66:69], v[74:77], v[32:47]
	ds_read_b128 v[66:69], v80 offset:20480
	s_waitcnt vmcnt(0) lgkmcnt(0)
	s_barrier
	s_waitcnt lgkmcnt(0)
	v_mfma_f32_32x32x16_bf16 v[16:31], v[66:69], v[70:73], v[16:31]
	v_mfma_f32_32x32x16_bf16 v[0:15], v[66:69], v[74:77], v[0:15]
	s_add_i32 s0, s15, 1
	s_mov_b32 s14, s2
	s_cmp_eq_u32 s15, 3
	s_cbranch_scc1 .LBB0_294
